# row-stat exchange: slots zeroed in P0, publish + direct slot polling (no counter atomic, no drain, one barrier less)
# baseline (speedup 1.0000x reference)
.LBB0_59:
	s_or_b64 exec, exec, s[4:5]
	s_waitcnt lgkmcnt(0)
	s_barrier
	s_and_saveexec_b64 s[74:75], s[40:41]
	s_cbranch_execz .LBB0_82
	v_add_u32_e32 v0, 0, v168
	v_add_u32_e32 v0, 0x26000, v0
	s_waitcnt lgkmcnt(0)
	ds_read_b128 v[178:181], v0
	s_ashr_i32 s69, s68, 31
	s_ashr_i32 s67, s66, 31
	v_readlane_b32 s8, v254, 57
	s_nop 3
	s_lshl_b32 s8, s8, 19
	s_sub_u32 s8, 0x120000, s8
	s_sub_u32 s72, s60, s8
	s_subb_u32 s73, s61, 0
	s_waitcnt lgkmcnt(0)
	v_mov_b32_e32 v182, v179
	v_mov_b32_e32 v183, v180
	v_mov_b32_e32 v179, v181
	v_pk_add_f32 v[178:179], v[182:183], v[178:179]
	v_lshl_add_u64 v[180:181], s[68:69], 0, v[136:137]
	v_pk_add_f32 v[178:179], v[178:179], v[178:179] op_sel:[0,1] op_sel_hi:[1,0]
	v_lshl_add_u64 v[182:183], v[180:181], 4, s[72:73]
	v_lshl_add_u64 v[180:181], s[66:67], 2, v[182:183]
	v_max_f32_e32 v0, 0x800000, v178
	global_store_dword v[180:181], v0, off sc1
	s_mov_b32 s8, 0x40000
.Lxpoll_0:
	global_load_dwordx4 v[178:181], v[182:183], off sc1
	s_waitcnt vmcnt(0)
	v_min3_u32 v0, v178, v179, v180
	v_min_u32_e32 v0, v0, v181
	v_cmp_eq_u32_e32 vcc, 0, v0
	s_and_b64 vcc, exec, vcc
	s_cbranch_scc0 .Lxrdy_0
	s_add_i32 s8, s8, -1
	s_cmp_lg_u32 s8, 0
	s_cbranch_scc0 .Lxrdy_0
	s_sleep 1
	s_branch .Lxpoll_0
.Lxrdy_0:
	v_add_f32_e32 v0, 0, v178
	v_add_f32_e32 v0, v0, v179
	v_add_f32_e32 v0, v0, v180
	v_add_f32_e32 v0, v0, v181
	v_fmamk_f32 v0, v0, 0x3a800000, v196
	v_mul_f32_e32 v1, 0x4f800000, v0
	v_cmp_gt_f32_e32 vcc, s31, v0
	s_nop 1
	v_cndmask_b32_e32 v0, v0, v1, vcc
	v_sqrt_f32_e32 v1, v0
	s_nop 0
	v_add_u32_e32 v2, -1, v1
	v_add_u32_e32 v178, 1, v1
	v_fma_f32 v179, -v2, v1, v0
	v_fma_f32 v180, -v178, v1, v0
	v_cmp_ge_f32_e64 s[4:5], 0, v179
	s_nop 1
	v_cndmask_b32_e64 v1, v1, v2, s[4:5]
	v_cmp_lt_f32_e64 s[4:5], 0, v180
	s_nop 1
	v_cndmask_b32_e64 v1, v1, v178, s[4:5]
	v_mul_f32_e32 v2, 0x37800000, v1
	v_cndmask_b32_e32 v1, v1, v2, vcc
	v_cmp_class_f32_e32 vcc, v0, v203
	s_nop 1
	v_cndmask_b32_e32 v0, v1, v0, vcc
	v_div_scale_f32 v1, s[4:5], v0, v0, 1.0
	v_rcp_f32_e32 v2, v1
	v_div_scale_f32 v178, vcc, 1.0, v0, 1.0
	v_fma_f32 v179, -v1, v2, 1.0
	v_fmac_f32_e32 v2, v179, v2
	v_mul_f32_e32 v179, v178, v2
	v_fma_f32 v180, -v1, v179, v178
	v_fmac_f32_e32 v179, v180, v2
	v_fma_f32 v1, -v1, v179, v178
	v_div_fmas_f32 v1, v1, v2, v179
	v_div_fixup_f32 v0, v1, v0, 1.0
	ds_write_b32 v173, v0
	s_branch .LBB0_82
.LBB0_78:
	v_mov_b32_e32 v6, v7
	v_mov_b32_e32 v5, v7
	v_mov_b32_e32 v4, v7
	v_mov_b32_e32 v11, v7
	v_mov_b32_e32 v10, v7
	v_mov_b32_e32 v9, v7
	v_mov_b32_e32 v8, v7
	v_mov_b32_e32 v15, v7
	v_mov_b32_e32 v14, v7
	v_mov_b32_e32 v13, v7
	v_mov_b32_e32 v12, v7
	v_mov_b32_e32 v19, v7
	v_mov_b32_e32 v18, v7
	v_mov_b32_e32 v17, v7
	v_mov_b32_e32 v16, v7
	v_mov_b32_e32 v23, v7
	v_mov_b32_e32 v22, v7
	v_mov_b32_e32 v21, v7
	v_mov_b32_e32 v20, v7
	v_mov_b32_e32 v27, v7
	v_mov_b32_e32 v26, v7
	v_mov_b32_e32 v25, v7
	v_mov_b32_e32 v24, v7
	v_mov_b32_e32 v31, v7
	v_mov_b32_e32 v30, v7
	v_mov_b32_e32 v29, v7
	v_mov_b32_e32 v28, v7
	v_mov_b32_e32 v35, v7
	v_mov_b32_e32 v34, v7
	v_mov_b32_e32 v33, v7
	v_mov_b32_e32 v32, v7
	v_mov_b32_e32 v39, v7
	v_mov_b32_e32 v38, v7
	v_mov_b32_e32 v37, v7
	v_mov_b32_e32 v36, v7
	v_mov_b32_e32 v43, v7
	v_mov_b32_e32 v42, v7
	v_mov_b32_e32 v41, v7
	v_mov_b32_e32 v40, v7
	v_mov_b32_e32 v47, v7
	v_mov_b32_e32 v46, v7
	v_mov_b32_e32 v45, v7
	v_mov_b32_e32 v44, v7
	v_mov_b32_e32 v51, v7
	v_mov_b32_e32 v50, v7
	v_mov_b32_e32 v49, v7
	v_mov_b32_e32 v48, v7
	v_mov_b32_e32 v55, v7
	v_mov_b32_e32 v54, v7
	v_mov_b32_e32 v53, v7
	v_mov_b32_e32 v52, v7
	v_mov_b32_e32 v59, v7
	v_mov_b32_e32 v58, v7
	v_mov_b32_e32 v57, v7
	v_mov_b32_e32 v56, v7
	v_mov_b32_e32 v67, v7
	v_mov_b32_e32 v66, v7
	v_mov_b32_e32 v65, v7
	v_mov_b32_e32 v64, v7
	v_mov_b32_e32 v63, v7
	v_mov_b32_e32 v62, v7
	v_mov_b32_e32 v61, v7
	v_mov_b32_e32 v60, v7
	s_and_b64 vcc, exec, s[50:51]
	s_cbranch_vccnz .LBB0_50
	s_branch .LBB0_51
.LBB0_82:
	s_or_b64 exec, exec, s[74:75]
	s_waitcnt lgkmcnt(0)
	s_barrier
	s_waitcnt vmcnt(0)
	v_pk_mul_f32 v[128:129], v[116:117], v[128:129]
	ds_read_b32 v116, v174
	v_lshlrev_b32_e32 v182, 16, v114
	v_and_b32_e32 v183, 0xffff0000, v114
	v_lshlrev_b32_e32 v114, 16, v115
	v_and_b32_e32 v115, 0xffff0000, v115
	v_pk_mul_f32 v[122:123], v[122:123], v[126:127]
	s_waitcnt lgkmcnt(0)
	v_pk_mul_f32 v[66:67], v[66:67], v[116:117] op_sel_hi:[1,0]
	v_lshlrev_b32_e32 v178, 16, v112
	v_and_b32_e32 v179, 0xffff0000, v112
	v_lshlrev_b32_e32 v180, 16, v113
	v_and_b32_e32 v181, 0xffff0000, v113
	v_pk_mul_f32 v[130:131], v[118:119], v[130:131]
	v_pk_mul_f32 v[120:121], v[120:121], v[124:125]
	v_lshl_add_u64 v[112:113], v[158:159], 2, s[26:27]
	v_pk_mul_f32 v[60:61], v[60:61], v[116:117] op_sel_hi:[1,0]
	v_pk_mul_f32 v[62:63], v[62:63], v[116:117] op_sel_hi:[1,0]
	v_pk_mul_f32 v[64:65], v[64:65], v[116:117] op_sel_hi:[1,0]
	v_pk_fma_f32 v[66:67], v[122:123], v[66:67], v[114:115]
	v_lshlrev_b64 v[114:115], 12, v[156:157]
	v_pk_fma_f32 v[62:63], v[130:131], v[62:63], v[180:181]
	v_pk_fma_f32 v[60:61], v[128:129], v[60:61], v[178:179]
	v_pk_fma_f32 v[64:65], v[120:121], v[64:65], v[182:183]
	s_mov_b64 s[4:5], -1
	s_and_b64 vcc, exec, s[58:59]
	v_lshl_add_u64 v[118:119], v[112:113], 0, v[114:115]
	s_cbranch_vccz .LBB0_84
	global_store_dwordx4 v[118:119], v[60:63], off
	global_store_dwordx4 v[118:119], v[64:67], off offset:64
	s_mov_b64 s[4:5], 0

.LBB0_124:
	s_or_b64 exec, exec, s[4:5]
	s_waitcnt lgkmcnt(0)
	s_barrier
	s_and_saveexec_b64 s[42:43], s[40:41]
	s_cbranch_execz .LBB0_146
	v_add_u32_e32 v0, 0, v168
	v_add_u32_e32 v0, 0x26000, v0
	s_waitcnt lgkmcnt(0)
	ds_read_b128 v[116:119], v0
	s_ashr_i32 s69, s68, 31
	s_ashr_i32 s67, s66, 31
	v_readlane_b32 s8, v254, 57
	s_nop 3
	s_lshl_b32 s8, s8, 19
	s_sub_u32 s8, 0x120000, s8
	s_sub_u32 s72, s60, s8
	s_subb_u32 s73, s61, 0
	s_waitcnt lgkmcnt(0)
	v_mov_b32_e32 v120, v117
	v_mov_b32_e32 v121, v118
	v_mov_b32_e32 v117, v119
	v_pk_add_f32 v[116:117], v[120:121], v[116:117]
	v_lshl_add_u64 v[118:119], v[138:139], 0, s[68:69]
	v_pk_add_f32 v[116:117], v[116:117], v[116:117] op_sel:[0,1] op_sel_hi:[1,0]
	v_lshl_add_u64 v[120:121], v[118:119], 4, s[72:73]
	v_lshl_add_u64 v[118:119], s[66:67], 2, v[120:121]
	v_max_f32_e32 v0, 0x800000, v116
	global_store_dword v[118:119], v0, off sc1
	s_mov_b32 s8, 0x40000
.Lxpoll_1:
	global_load_dwordx4 v[116:119], v[120:121], off sc1
	s_waitcnt vmcnt(0)
	v_min3_u32 v0, v116, v117, v118
	v_min_u32_e32 v0, v0, v119
	v_cmp_eq_u32_e32 vcc, 0, v0
	s_and_b64 vcc, exec, vcc
	s_cbranch_scc0 .Lxrdy_1
	s_add_i32 s8, s8, -1
	s_cmp_lg_u32 s8, 0
	s_cbranch_scc0 .Lxrdy_1
	s_sleep 1
	s_branch .Lxpoll_1
.Lxrdy_1:
	v_add_f32_e32 v0, 0, v116
	v_add_f32_e32 v0, v0, v117
	v_add_f32_e32 v0, v0, v118
	v_add_f32_e32 v0, v0, v119
	v_fmamk_f32 v0, v0, 0x3a800000, v196
	v_mul_f32_e32 v1, 0x4f800000, v0
	v_cmp_gt_f32_e32 vcc, s31, v0
	s_nop 1
	v_cndmask_b32_e32 v0, v0, v1, vcc
	v_sqrt_f32_e32 v1, v0
	s_nop 0
	v_add_u32_e32 v2, -1, v1
	v_add_u32_e32 v116, 1, v1
	v_fma_f32 v117, -v2, v1, v0
	v_fma_f32 v118, -v116, v1, v0
	v_cmp_ge_f32_e64 s[4:5], 0, v117
	s_nop 1
	v_cndmask_b32_e64 v1, v1, v2, s[4:5]
	v_cmp_lt_f32_e64 s[4:5], 0, v118
	s_nop 1
	v_cndmask_b32_e64 v1, v1, v116, s[4:5]
	v_mul_f32_e32 v2, 0x37800000, v1
	v_cndmask_b32_e32 v1, v1, v2, vcc
	v_cmp_class_f32_e32 vcc, v0, v203
	s_nop 1
	v_cndmask_b32_e32 v0, v1, v0, vcc
	v_div_scale_f32 v1, s[4:5], v0, v0, 1.0
	v_rcp_f32_e32 v2, v1
	v_div_scale_f32 v116, vcc, 1.0, v0, 1.0
	v_fma_f32 v117, -v1, v2, 1.0
	v_fmac_f32_e32 v2, v117, v2
	v_mul_f32_e32 v117, v116, v2
	v_fma_f32 v118, -v1, v117, v116
	v_fmac_f32_e32 v117, v118, v2
	v_fma_f32 v1, -v1, v117, v116
	v_div_fmas_f32 v1, v1, v2, v117
	v_div_fixup_f32 v0, v1, v0, 1.0
	ds_write_b32 v173, v0
	s_branch .LBB0_146

.LBB0_443:
	s_or_b64 exec, exec, s[4:5]
	s_waitcnt lgkmcnt(0)
	s_barrier
	s_and_saveexec_b64 s[78:79], s[40:41]
	s_cbranch_execz .LBB0_466
	v_add_u32_e32 v0, 0, v222
	v_add_u32_e32 v0, 0x26000, v0
	s_waitcnt lgkmcnt(0)
	ds_read_b128 v[232:235], v0
	s_ashr_i32 s75, s74, 31
	s_ashr_i32 s71, s70, 31
	v_readlane_b32 s8, v254, 57
	s_nop 3
	s_lshl_b32 s8, s8, 19
	s_sub_u32 s8, 0x160000, s8
	s_sub_u32 s76, s64, s8
	s_subb_u32 s77, s65, 0
	s_waitcnt lgkmcnt(0)
	v_mov_b32_e32 v236, v233
	v_mov_b32_e32 v237, v234
	v_mov_b32_e32 v233, v235
	v_pk_add_f32 v[232:233], v[236:237], v[232:233]
	v_lshl_add_u64 v[234:235], s[74:75], 0, v[168:169]
	v_pk_add_f32 v[232:233], v[232:233], v[232:233] op_sel:[0,1] op_sel_hi:[1,0]
	v_lshl_add_u64 v[236:237], v[234:235], 4, s[76:77]
	v_lshl_add_u64 v[234:235], s[70:71], 2, v[236:237]
	v_max_f32_e32 v0, 0x800000, v232
	global_store_dword v[234:235], v0, off sc1
	s_mov_b32 s8, 0x40000
.Lxpoll_2:
	global_load_dwordx4 v[232:235], v[236:237], off sc1
	s_waitcnt vmcnt(0)
	v_min3_u32 v0, v232, v233, v234
	v_min_u32_e32 v0, v0, v235
	v_cmp_eq_u32_e32 vcc, 0, v0
	s_and_b64 vcc, exec, vcc
	s_cbranch_scc0 .Lxrdy_2
	s_add_i32 s8, s8, -1
	s_cmp_lg_u32 s8, 0
	s_cbranch_scc0 .Lxrdy_2
	s_sleep 1
	s_branch .Lxpoll_2
.Lxrdy_2:
	v_add_f32_e32 v0, 0, v232
	v_add_f32_e32 v0, v0, v233
	v_add_f32_e32 v0, v0, v234
	v_add_f32_e32 v0, v0, v235
	v_fmamk_f32 v0, v0, 0x3a800000, v196
	v_mul_f32_e32 v1, 0x4f800000, v0
	v_cmp_gt_f32_e32 vcc, s31, v0
	s_nop 1
	v_cndmask_b32_e32 v0, v0, v1, vcc
	v_sqrt_f32_e32 v1, v0
	s_nop 0
	v_add_u32_e32 v2, -1, v1
	v_add_u32_e32 v197, 1, v1
	v_fma_f32 v198, -v2, v1, v0
	v_fma_f32 v201, -v197, v1, v0
	v_cmp_ge_f32_e64 s[4:5], 0, v198
	s_nop 1
	v_cndmask_b32_e64 v1, v1, v2, s[4:5]
	v_cmp_lt_f32_e64 s[4:5], 0, v201
	s_nop 1
	v_cndmask_b32_e64 v1, v1, v197, s[4:5]
	v_mul_f32_e32 v2, 0x37800000, v1
	v_cndmask_b32_e32 v1, v1, v2, vcc
	v_cmp_class_f32_e32 vcc, v0, v203
	s_nop 1
	v_cndmask_b32_e32 v0, v1, v0, vcc
	v_div_scale_f32 v1, s[4:5], v0, v0, 1.0
	v_rcp_f32_e32 v2, v1
	v_div_scale_f32 v197, vcc, 1.0, v0, 1.0
	v_fma_f32 v198, -v1, v2, 1.0
	v_fmac_f32_e32 v2, v198, v2
	v_mul_f32_e32 v198, v197, v2
	v_fma_f32 v201, -v1, v198, v197
	v_fmac_f32_e32 v198, v201, v2
	v_fma_f32 v1, -v1, v198, v197
	v_div_fmas_f32 v1, v1, v2, v198
	v_div_fixup_f32 v0, v1, v0, 1.0
	ds_write_b32 v227, v0
	s_branch .LBB0_466
.LBB0_462:
	v_mov_b32_e32 v6, v7
	v_mov_b32_e32 v5, v7
	v_mov_b32_e32 v4, v7
	v_mov_b32_e32 v11, v7
	v_mov_b32_e32 v10, v7
	v_mov_b32_e32 v9, v7
	v_mov_b32_e32 v8, v7
	v_mov_b32_e32 v15, v7
	v_mov_b32_e32 v14, v7
	v_mov_b32_e32 v13, v7
	v_mov_b32_e32 v12, v7
	v_mov_b32_e32 v19, v7
	v_mov_b32_e32 v18, v7
	v_mov_b32_e32 v17, v7
	v_mov_b32_e32 v16, v7
	v_mov_b32_e32 v23, v7
	v_mov_b32_e32 v22, v7
	v_mov_b32_e32 v21, v7
	v_mov_b32_e32 v20, v7
	v_mov_b32_e32 v27, v7
	v_mov_b32_e32 v26, v7
	v_mov_b32_e32 v25, v7
	v_mov_b32_e32 v24, v7
	v_mov_b32_e32 v31, v7
	v_mov_b32_e32 v30, v7
	v_mov_b32_e32 v29, v7
	v_mov_b32_e32 v28, v7
	v_mov_b32_e32 v35, v7
	v_mov_b32_e32 v34, v7
	v_mov_b32_e32 v33, v7
	v_mov_b32_e32 v32, v7
	v_mov_b32_e32 v39, v7
	v_mov_b32_e32 v38, v7
	v_mov_b32_e32 v37, v7
	v_mov_b32_e32 v36, v7
	v_mov_b32_e32 v43, v7
	v_mov_b32_e32 v42, v7
	v_mov_b32_e32 v41, v7
	v_mov_b32_e32 v40, v7
	v_mov_b32_e32 v47, v7
	v_mov_b32_e32 v46, v7
	v_mov_b32_e32 v45, v7
	v_mov_b32_e32 v44, v7
	v_mov_b32_e32 v51, v7
	v_mov_b32_e32 v50, v7
	v_mov_b32_e32 v49, v7
	v_mov_b32_e32 v48, v7
	v_mov_b32_e32 v55, v7
	v_mov_b32_e32 v54, v7
	v_mov_b32_e32 v53, v7
	v_mov_b32_e32 v52, v7
	v_mov_b32_e32 v59, v7
	v_mov_b32_e32 v58, v7
	v_mov_b32_e32 v57, v7
	v_mov_b32_e32 v56, v7
	v_mov_b32_e32 v63, v7
	v_mov_b32_e32 v62, v7
	v_mov_b32_e32 v61, v7
	v_mov_b32_e32 v60, v7
	v_mov_b32_e32 v67, v7
	v_mov_b32_e32 v66, v7
	v_mov_b32_e32 v65, v7
	v_mov_b32_e32 v64, v7
	s_and_b64 vcc, exec, s[52:53]
	s_cbranch_vccnz .LBB0_418
	s_branch .LBB0_419
.LBB0_466:
	s_or_b64 exec, exec, s[78:79]
	s_waitcnt lgkmcnt(0)
	s_barrier
	s_waitcnt vmcnt(0)
	v_pk_mul_f32 v[156:157], v[152:153], v[156:157]
	ds_read_b32 v152, v228
	v_pk_mul_f32 v[162:163], v[150:151], v[162:163]
	v_pk_mul_f32 v[160:161], v[148:149], v[160:161]
	v_pk_mul_f32 v[154:155], v[154:155], v[158:159]
	v_lshl_add_u64 v[150:151], v[188:189], 2, s[26:27]
	s_waitcnt lgkmcnt(0)
	v_pk_mul_f32 v[64:65], v[64:65], v[152:153] op_sel_hi:[1,0]
	v_pk_mul_f32 v[66:67], v[66:67], v[152:153] op_sel_hi:[1,0]
	v_pk_mul_f32 v[60:61], v[60:61], v[152:153] op_sel_hi:[1,0]
	v_pk_mul_f32 v[62:63], v[62:63], v[152:153] op_sel_hi:[1,0]
	v_pk_fma_f32 v[66:67], v[162:163], v[66:67], v[106:107]
	v_pk_fma_f32 v[64:65], v[160:161], v[64:65], v[104:105]
	v_pk_fma_f32 v[62:63], v[154:155], v[62:63], v[102:103]
	v_pk_fma_f32 v[60:61], v[156:157], v[60:61], v[100:101]
	s_mov_b64 s[4:5], -1
	s_and_b64 vcc, exec, s[62:63]
	s_cbranch_vccz .LBB0_468
	v_lshlrev_b64 v[100:101], 12, v[178:179]
	v_lshl_add_u64 v[100:101], v[150:151], 0, v[100:101]
	global_store_dwordx4 v[100:101], v[64:67], off
	global_store_dwordx4 v[100:101], v[60:63], off offset:64
	s_mov_b64 s[4:5], 0

.LBB0_505:
	s_or_b64 exec, exec, s[4:5]
	s_waitcnt lgkmcnt(0)
	s_barrier
	s_and_saveexec_b64 s[42:43], s[40:41]
	s_cbranch_execz .LBB0_530
	v_add_u32_e32 v0, 0, v222
	v_add_u32_e32 v0, 0x26000, v0
	s_waitcnt lgkmcnt(0)
	ds_read_b128 v[120:123], v0
	s_ashr_i32 s75, s74, 31
	s_ashr_i32 s71, s70, 31
	v_readlane_b32 s8, v254, 57
	s_nop 3
	s_lshl_b32 s8, s8, 19
	s_sub_u32 s8, 0x160000, s8
	s_sub_u32 s76, s64, s8
	s_subb_u32 s77, s65, 0
	s_waitcnt lgkmcnt(0)
	v_mov_b32_e32 v124, v121
	v_mov_b32_e32 v125, v122
	v_mov_b32_e32 v121, v123
	v_pk_add_f32 v[120:121], v[124:125], v[120:121]
	v_lshl_add_u64 v[122:123], v[170:171], 0, s[74:75]
	v_pk_add_f32 v[120:121], v[120:121], v[120:121] op_sel:[0,1] op_sel_hi:[1,0]
	v_lshl_add_u64 v[124:125], v[122:123], 4, s[76:77]
	v_lshl_add_u64 v[122:123], s[70:71], 2, v[124:125]
	v_max_f32_e32 v0, 0x800000, v120
	global_store_dword v[122:123], v0, off sc1
	s_mov_b32 s8, 0x40000
.Lxpoll_3:
	global_load_dwordx4 v[120:123], v[124:125], off sc1
	s_waitcnt vmcnt(0)
	v_min3_u32 v0, v120, v121, v122
	v_min_u32_e32 v0, v0, v123
	v_cmp_eq_u32_e32 vcc, 0, v0
	s_and_b64 vcc, exec, vcc
	s_cbranch_scc0 .Lxrdy_3
	s_add_i32 s8, s8, -1
	s_cmp_lg_u32 s8, 0
	s_cbranch_scc0 .Lxrdy_3
	s_sleep 1
	s_branch .Lxpoll_3
.Lxrdy_3:
	v_add_f32_e32 v0, 0, v120
	v_add_f32_e32 v0, v0, v121
	v_add_f32_e32 v0, v0, v122
	v_add_f32_e32 v0, v0, v123
	v_fmamk_f32 v0, v0, 0x3a800000, v196
	v_mul_f32_e32 v1, 0x4f800000, v0
	v_cmp_gt_f32_e32 vcc, s31, v0
	s_nop 1
	v_cndmask_b32_e32 v0, v0, v1, vcc
	v_sqrt_f32_e32 v1, v0
	s_nop 0
	v_add_u32_e32 v2, -1, v1
	v_add_u32_e32 v120, 1, v1
	v_fma_f32 v121, -v2, v1, v0
	v_fma_f32 v122, -v120, v1, v0
	v_cmp_ge_f32_e64 s[4:5], 0, v121
	s_nop 1
	v_cndmask_b32_e64 v1, v1, v2, s[4:5]
	v_cmp_lt_f32_e64 s[4:5], 0, v122
	s_nop 1
	v_cndmask_b32_e64 v1, v1, v120, s[4:5]
	v_mul_f32_e32 v2, 0x37800000, v1
	v_cndmask_b32_e32 v1, v1, v2, vcc
	v_cmp_class_f32_e32 vcc, v0, v203
	s_nop 1
	v_cndmask_b32_e32 v0, v1, v0, vcc
	v_div_scale_f32 v1, s[4:5], v0, v0, 1.0
	v_rcp_f32_e32 v2, v1
	v_div_scale_f32 v120, vcc, 1.0, v0, 1.0
	v_fma_f32 v121, -v1, v2, 1.0
	v_fmac_f32_e32 v2, v121, v2
	v_mul_f32_e32 v121, v120, v2
	v_fma_f32 v122, -v1, v121, v120
	v_fmac_f32_e32 v121, v122, v2
	v_fma_f32 v1, -v1, v121, v120
	v_div_fmas_f32 v1, v1, v2, v121
	v_div_fixup_f32 v0, v1, v0, 1.0
	ds_write_b32 v227, v0
	s_branch .LBB0_530

.LBB0_526:
	s_andn2_b64 vcc, exec, s[68:69]
	s_mov_b64 s[4:5], -1
	s_cbranch_vccnz .LBB0_406
	s_branch .LBB0_531
.LBB0_530:
	s_or_b64 exec, exec, s[42:43]
	s_waitcnt vmcnt(11)
	v_pk_add_f32 v[110:111], v[110:111], 1.0 op_sel_hi:[1,0]
	v_pk_add_f32 v[108:109], v[108:109], 1.0 op_sel_hi:[1,0]
	s_waitcnt vmcnt(9)
	v_pk_mul_f32 v[98:99], v[98:99], v[110:111]
	s_waitcnt vmcnt(7)
	v_pk_add_f32 v[110:111], v[112:113], 1.0 op_sel_hi:[1,0]
	v_pk_mul_f32 v[96:97], v[96:97], v[108:109]
	v_pk_add_f32 v[108:109], v[114:115], 1.0 op_sel_hi:[1,0]
	v_pk_mul_f32 v[110:111], v[88:89], v[110:111]
	s_waitcnt vmcnt(5)
	v_pk_add_f32 v[88:89], v[102:103], 1.0 op_sel_hi:[1,0]
	s_waitcnt lgkmcnt(0)
	s_barrier
	v_pk_mul_f32 v[108:109], v[90:91], v[108:109]
	v_pk_add_f32 v[90:91], v[100:101], 1.0 op_sel_hi:[1,0]
	s_waitcnt vmcnt(3)
	v_pk_mul_f32 v[88:89], v[94:95], v[88:89]
	s_waitcnt vmcnt(1)
	v_pk_add_f32 v[94:95], v[104:105], 1.0 op_sel_hi:[1,0]
	ds_read_b32 v2, v228
	ds_read_b32 v100, v229
	ds_read_b32 v102, v230
	ds_read_b32 v104, v231
	v_pk_mul_f32 v[90:91], v[92:93], v[90:91]
	v_pk_add_f32 v[92:93], v[106:107], 1.0 op_sel_hi:[1,0]
	v_pk_mul_f32 v[84:85], v[84:85], v[94:95]
	v_pk_mul_f32 v[86:87], v[86:87], v[92:93]
	s_waitcnt lgkmcnt(3)
	v_pk_mul_f32 v[66:67], v[66:67], v[2:3] op_sel_hi:[1,0]
	v_pk_mul_f32 v[64:65], v[64:65], v[2:3] op_sel_hi:[1,0]
	v_pk_mul_f32 v[62:63], v[62:63], v[2:3] op_sel_hi:[1,0]
	v_pk_mul_f32 v[60:61], v[60:61], v[2:3] op_sel_hi:[1,0]
	s_waitcnt lgkmcnt(2)
	v_pk_mul_f32 v[58:59], v[58:59], v[100:101] op_sel_hi:[1,0]
	v_pk_mul_f32 v[56:57], v[56:57], v[100:101] op_sel_hi:[1,0]
	v_pk_mul_f32 v[54:55], v[54:55], v[100:101] op_sel_hi:[1,0]
	v_pk_mul_f32 v[52:53], v[52:53], v[100:101] op_sel_hi:[1,0]
	s_waitcnt lgkmcnt(1)
	v_pk_mul_f32 v[50:51], v[50:51], v[102:103] op_sel_hi:[1,0]
	v_pk_mul_f32 v[48:49], v[48:49], v[102:103] op_sel_hi:[1,0]
	v_pk_mul_f32 v[46:47], v[46:47], v[102:103] op_sel_hi:[1,0]
	v_pk_mul_f32 v[44:45], v[44:45], v[102:103] op_sel_hi:[1,0]
	s_waitcnt lgkmcnt(0)
	v_pk_mul_f32 v[42:43], v[42:43], v[104:105] op_sel_hi:[1,0]
	v_pk_mul_f32 v[40:41], v[40:41], v[104:105] op_sel_hi:[1,0]
	v_pk_mul_f32 v[38:39], v[38:39], v[104:105] op_sel_hi:[1,0]
	v_pk_mul_f32 v[36:37], v[36:37], v[104:105] op_sel_hi:[1,0]
	v_pk_mul_f32 v[34:35], v[34:35], v[2:3] op_sel_hi:[1,0]
	v_pk_mul_f32 v[32:33], v[32:33], v[2:3] op_sel_hi:[1,0]
	v_pk_mul_f32 v[30:31], v[30:31], v[2:3] op_sel_hi:[1,0]
	v_pk_mul_f32 v[28:29], v[28:29], v[2:3] op_sel_hi:[1,0]
	v_pk_mul_f32 v[26:27], v[26:27], v[100:101] op_sel_hi:[1,0]
	v_pk_mul_f32 v[24:25], v[24:25], v[100:101] op_sel_hi:[1,0]
	v_pk_mul_f32 v[22:23], v[22:23], v[100:101] op_sel_hi:[1,0]
	v_pk_mul_f32 v[20:21], v[20:21], v[100:101] op_sel_hi:[1,0]
	v_pk_mul_f32 v[18:19], v[18:19], v[102:103] op_sel_hi:[1,0]
	v_pk_mul_f32 v[16:17], v[16:17], v[102:103] op_sel_hi:[1,0]
	v_pk_mul_f32 v[14:15], v[14:15], v[102:103] op_sel_hi:[1,0]
	v_pk_mul_f32 v[12:13], v[12:13], v[102:103] op_sel_hi:[1,0]
	v_pk_mul_f32 v[10:11], v[10:11], v[104:105] op_sel_hi:[1,0]
	v_pk_mul_f32 v[8:9], v[8:9], v[104:105] op_sel_hi:[1,0]
	v_pk_mul_f32 v[6:7], v[6:7], v[104:105] op_sel_hi:[1,0]
	v_pk_mul_f32 v[4:5], v[4:5], v[104:105] op_sel_hi:[1,0]
	v_pk_fma_f32 v[66:67], v[98:99], v[66:67], v[78:79]
	v_pk_fma_f32 v[64:65], v[96:97], v[64:65], v[76:77]
	v_pk_fma_f32 v[62:63], v[108:109], v[62:63], v[82:83]
	v_pk_fma_f32 v[60:61], v[110:111], v[60:61], v[80:81]
	v_pk_fma_f32 v[58:59], v[98:99], v[58:59], v[78:79]
	v_pk_fma_f32 v[56:57], v[96:97], v[56:57], v[76:77]
	v_pk_fma_f32 v[54:55], v[108:109], v[54:55], v[82:83]
	v_pk_fma_f32 v[52:53], v[110:111], v[52:53], v[80:81]
	v_pk_fma_f32 v[50:51], v[98:99], v[50:51], v[78:79]
	v_pk_fma_f32 v[48:49], v[96:97], v[48:49], v[76:77]
	v_pk_fma_f32 v[46:47], v[108:109], v[46:47], v[82:83]
	v_pk_fma_f32 v[44:45], v[110:111], v[44:45], v[80:81]
	v_pk_fma_f32 v[42:43], v[98:99], v[42:43], v[78:79]
	v_pk_fma_f32 v[40:41], v[96:97], v[40:41], v[76:77]
	v_pk_fma_f32 v[38:39], v[108:109], v[38:39], v[82:83]
	v_pk_fma_f32 v[36:37], v[110:111], v[36:37], v[80:81]
	v_pk_fma_f32 v[34:35], v[88:89], v[34:35], v[70:71]
	v_pk_fma_f32 v[32:33], v[90:91], v[32:33], v[68:69]
	s_waitcnt vmcnt(0)
	v_pk_fma_f32 v[30:31], v[86:87], v[30:31], v[74:75]
	v_pk_fma_f32 v[28:29], v[84:85], v[28:29], v[72:73]
	v_pk_fma_f32 v[26:27], v[88:89], v[26:27], v[70:71]
	v_pk_fma_f32 v[24:25], v[90:91], v[24:25], v[68:69]
	v_pk_fma_f32 v[22:23], v[86:87], v[22:23], v[74:75]
	v_pk_fma_f32 v[20:21], v[84:85], v[20:21], v[72:73]
	v_pk_fma_f32 v[18:19], v[88:89], v[18:19], v[70:71]
	v_pk_fma_f32 v[16:17], v[90:91], v[16:17], v[68:69]
	v_pk_fma_f32 v[14:15], v[86:87], v[14:15], v[74:75]
	v_pk_fma_f32 v[12:13], v[84:85], v[12:13], v[72:73]
	v_pk_fma_f32 v[10:11], v[88:89], v[10:11], v[70:71]
	v_pk_fma_f32 v[8:9], v[90:91], v[8:9], v[68:69]
	v_pk_fma_f32 v[6:7], v[86:87], v[6:7], v[74:75]
	v_pk_fma_f32 v[4:5], v[84:85], v[4:5], v[72:73]
	v_lshl_add_u64 v[92:93], s[72:73], 1, v[176:177]
	v_lshlrev_b64 v[94:95], 11, v[178:179]
	v_cvt_pk_bf16_f32 v64, v64, v65
	v_cvt_pk_bf16_f32 v65, v66, v67
	v_cvt_pk_bf16_f32 v66, v60, v61
	v_cvt_pk_bf16_f32 v67, v62, v63
	v_lshlrev_b64 v[60:61], 11, v[148:149]
	v_cvt_pk_bf16_f32 v56, v56, v57
	v_cvt_pk_bf16_f32 v57, v58, v59
	v_cvt_pk_bf16_f32 v58, v52, v53
	v_cvt_pk_bf16_f32 v59, v54, v55
	v_lshlrev_b64 v[52:53], 11, v[116:117]
	v_cvt_pk_bf16_f32 v48, v48, v49
	v_cvt_pk_bf16_f32 v49, v50, v51
	v_cvt_pk_bf16_f32 v50, v44, v45
	v_cvt_pk_bf16_f32 v51, v46, v47
	v_lshlrev_b64 v[44:45], 11, v[118:119]
	v_cvt_pk_bf16_f32 v40, v40, v41
	v_cvt_pk_bf16_f32 v41, v42, v43
	v_cvt_pk_bf16_f32 v42, v36, v37
	v_cvt_pk_bf16_f32 v43, v38, v39
	v_cvt_pk_bf16_f32 v32, v32, v33
	v_cvt_pk_bf16_f32 v33, v34, v35
	v_cvt_pk_bf16_f32 v34, v28, v29
	v_cvt_pk_bf16_f32 v35, v30, v31
	v_cvt_pk_bf16_f32 v24, v24, v25
	v_cvt_pk_bf16_f32 v25, v26, v27
	v_cvt_pk_bf16_f32 v26, v20, v21
	v_cvt_pk_bf16_f32 v27, v22, v23
	v_cvt_pk_bf16_f32 v16, v16, v17
	v_cvt_pk_bf16_f32 v17, v18, v19
	v_cvt_pk_bf16_f32 v18, v12, v13
	v_cvt_pk_bf16_f32 v19, v14, v15
	v_cvt_pk_bf16_f32 v8, v8, v9
	v_cvt_pk_bf16_f32 v9, v10, v11
	v_cvt_pk_bf16_f32 v10, v4, v5
	v_cvt_pk_bf16_f32 v11, v6, v7
	v_lshl_add_u64 v[94:95], v[92:93], 0, v[94:95]
	v_permlane16_swap_b32_e32 v64, v66
	v_permlane16_swap_b32_e32 v65, v67
	v_lshl_add_u64 v[60:61], v[92:93], 0, v[60:61]
	v_permlane16_swap_b32_e32 v56, v58
	v_permlane16_swap_b32_e32 v57, v59
	v_lshl_add_u64 v[52:53], v[92:93], 0, v[52:53]
	v_permlane16_swap_b32_e32 v48, v50
	v_permlane16_swap_b32_e32 v49, v51
	v_lshl_add_u64 v[44:45], v[92:93], 0, v[44:45]
	v_permlane16_swap_b32_e32 v40, v42
	v_permlane16_swap_b32_e32 v41, v43
	v_permlane16_swap_b32_e32 v32, v34
	v_permlane16_swap_b32_e32 v33, v35
	v_permlane16_swap_b32_e32 v24, v26
	v_permlane16_swap_b32_e32 v25, v27
	v_permlane16_swap_b32_e32 v16, v18
	v_permlane16_swap_b32_e32 v17, v19
	v_permlane16_swap_b32_e32 v8, v10
	v_permlane16_swap_b32_e32 v9, v11
	global_store_dwordx4 v[94:95], v[64:67], off
	global_store_dwordx4 v[60:61], v[56:59], off
	global_store_dwordx4 v[52:53], v[48:51], off
	global_store_dwordx4 v[44:45], v[40:43], off
	global_store_dwordx4 v[94:95], v[32:35], off offset:256
	global_store_dwordx4 v[60:61], v[24:27], off offset:256
	global_store_dwordx4 v[52:53], v[16:19], off offset:256
	global_store_dwordx4 v[44:45], v[8:11], off offset:256
	s_andn2_b64 vcc, exec, s[68:69]
	s_mov_b64 s[4:5], -1
	s_cbranch_vccnz .LBB0_406

.LBB0_1752:
	s_and_b64 vcc, exec, s[8:9]
	s_cbranch_vccz .LBB0_1924
	v_lshl_add_u32 v4, s16, 9, v202
	v_mov_b32_e32 v6, 0
	v_mov_b32_e32 v7, 0
	v_cmp_gt_u32_e32 vcc, 0x1c000, v4
	s_and_saveexec_b64 s[4:5], vcc
	v_lshlrev_b32_e32 v4, 3, v4
	v_add_u32_e32 v4, 0x20000, v4
	global_store_dwordx2 v4, v[6:7], s[10:11] sc1
	s_or_b64 exec, exec, s[4:5]
	s_mov_b64 s[8:9], s[0:1]
	v_mov_b32_e32 v69, v202
	s_movk_i32 s4, 0x1400
	s_nop 0
	v_readfirstlane_b32 s83, v69
	v_cmp_gt_i32_e32 vcc, s4, v69
	s_and_saveexec_b64 s[4:5], vcc
	s_cbranch_execz .LBB0_1760
	v_lshl_add_u32 v6, v69, 2, 0
	s_mov_b64 s[6:7], 0
	v_mov_b32_e32 v7, v69
	s_branch .LBB0_1756
